# gate-up epilogue stores of the FFN hidden tile use write-through (sc1) so they do not occupy L2
# speedup vs baseline: 1.0120x; 1.0062x over previous
; __device__ __forceinline__ unsigned cvt_pk_bf16(float lo, float hi) { unsigned r; asm volatile("v_cvt_pk_bf16_f32 %0, %1, %2" : "=v"(r) : "v"(lo), "v"(hi)); return r; }
; __device__ __forceinline__ float silu_f(float g) { return g * __builtin_amdgcn_rcpf(1.0f + __builtin_amdgcn_exp2f(g * -1.4426950408889634f)); }
;     __device__ __forceinline__ void operator()(const f32x4 (&acc)[2][2][4][2], const Unit& u, int wr, int wc, int fr, int fq) const {
;     ...
;             for (int m = 0; m < 4; ++m) { const int row = row0 + ai * HALF + m * 16; const float rs = rsv[ai][m];
;                 f32x4 g0 = acc[ai][0][m][0] * rs, g1 = acc[ai][0][m][1] * rs; const f32x4 t0 = acc[ai][1][m][0] * rs, t1 = acc[ai][1][m][1] * rs;
;                 if (silu) {
; #pragma unroll
;                     for (int j = 0; j < 4; ++j) { g0[j] = silu_f(g0[j]); g1[j] = silu_f(g1[j]); } }
;                 g0 = g0 * t0; g1 = g1 * t1;
;                 u32x4 w; w.x = cvt_pk_bf16(g0[0], g0[1]); w.y = cvt_pk_bf16(g0[2], g0[3]); w.z = cvt_pk_bf16(g1[0], g1[1]); w.w = cvt_pk_bf16(g1[2], g1[3]);
;                 *(u32x4*)(O + (size_t)row * ldc + col0 + (size_t)(row >> 12) * adj) = w; }
.Lep_have_rs:
	v_pk_mul_f32 v[146:147], v[142:143], v[240:241] op_sel_hi:[1,0]
	v_pk_mul_f32 v[148:149], v[144:145], v[240:241] op_sel_hi:[1,0]
	v_pk_mul_f32 v[150:151], v[138:139], v[240:241] op_sel_hi:[1,0]
	v_pk_mul_f32 v[152:153], v[140:141], v[240:241] op_sel_hi:[1,0]
	v_exp_f32_e32 v146, v146
	v_exp_f32_e32 v147, v147
	v_exp_f32_e32 v148, v148
	v_exp_f32_e32 v149, v149
	v_exp_f32_e32 v150, v150
	v_exp_f32_e32 v151, v151
	v_exp_f32_e32 v152, v152
	v_exp_f32_e32 v153, v153
	v_pk_mul_f32 v[142:143], v[142:143], v[130:131]
	v_pk_mul_f32 v[144:145], v[144:145], v[132:133]
	v_pk_mul_f32 v[138:139], v[138:139], v[126:127]
	v_pk_mul_f32 v[140:141], v[140:141], v[128:129]
	v_pk_fma_f32 v[146:147], v[146:147], v[240:241], v[240:241] op_sel:[0,1,1] op_sel_hi:[1,1,1]
	v_pk_fma_f32 v[148:149], v[148:149], v[240:241], v[240:241] op_sel:[0,1,1] op_sel_hi:[1,1,1]
	v_pk_fma_f32 v[150:151], v[150:151], v[240:241], v[240:241] op_sel:[0,1,1] op_sel_hi:[1,1,1]
	v_pk_fma_f32 v[152:153], v[152:153], v[240:241], v[240:241] op_sel:[0,1,1] op_sel_hi:[1,1,1]
	v_rcp_f32_e32 v146, v146
	v_rcp_f32_e32 v147, v147
	v_rcp_f32_e32 v148, v148
	v_rcp_f32_e32 v149, v149
	v_rcp_f32_e32 v150, v150
	v_rcp_f32_e32 v151, v151
	v_rcp_f32_e32 v152, v152
	v_rcp_f32_e32 v153, v153
	v_pk_mul_f32 v[154:155], v[122:123], v[242:243] op_sel_hi:[1,0]
	v_pk_mul_f32 v[156:157], v[124:125], v[242:243] op_sel_hi:[1,0]
	v_pk_mul_f32 v[158:159], v[118:119], v[242:243] op_sel_hi:[1,0]
	v_pk_mul_f32 v[160:161], v[120:121], v[242:243] op_sel_hi:[1,0]
	v_pk_mul_f32 v[142:143], v[142:143], v[146:147]
	v_pk_mul_f32 v[144:145], v[144:145], v[148:149]
	v_pk_mul_f32 v[138:139], v[138:139], v[150:151]
	v_pk_mul_f32 v[140:141], v[140:141], v[152:153]
	v_cvt_pk_bf16_f32 v162, v142, v143
	v_cvt_pk_bf16_f32 v163, v144, v145
	v_cvt_pk_bf16_f32 v164, v138, v139
	v_cvt_pk_bf16_f32 v165, v140, v141
	global_store_dwordx4 v190, v[162:165], s[10:11] sc1
	v_add_u32_e32 v190, s30, v190
	v_exp_f32_e32 v154, v154
	v_exp_f32_e32 v155, v155
	v_exp_f32_e32 v156, v156
	v_exp_f32_e32 v157, v157
	v_exp_f32_e32 v158, v158
	v_exp_f32_e32 v159, v159
	v_exp_f32_e32 v160, v160
	v_exp_f32_e32 v161, v161
	v_pk_mul_f32 v[122:123], v[122:123], v[110:111]
	v_pk_mul_f32 v[124:125], v[124:125], v[112:113]
	v_pk_mul_f32 v[118:119], v[118:119], v[106:107]
	v_pk_mul_f32 v[120:121], v[120:121], v[108:109]
	v_pk_fma_f32 v[154:155], v[154:155], v[242:243], v[242:243] op_sel:[0,1,1] op_sel_hi:[1,1,1]
	v_pk_fma_f32 v[156:157], v[156:157], v[242:243], v[242:243] op_sel:[0,1,1] op_sel_hi:[1,1,1]
	v_pk_fma_f32 v[158:159], v[158:159], v[242:243], v[242:243] op_sel:[0,1,1] op_sel_hi:[1,1,1]
	v_pk_fma_f32 v[160:161], v[160:161], v[242:243], v[242:243] op_sel:[0,1,1] op_sel_hi:[1,1,1]
	v_rcp_f32_e32 v154, v154
	v_rcp_f32_e32 v155, v155
	v_rcp_f32_e32 v156, v156
	v_rcp_f32_e32 v157, v157
	v_rcp_f32_e32 v158, v158
	v_rcp_f32_e32 v159, v159
	v_rcp_f32_e32 v160, v160
	v_rcp_f32_e32 v161, v161
	v_pk_mul_f32 v[146:147], v[102:103], v[244:245] op_sel_hi:[1,0]
	v_pk_mul_f32 v[148:149], v[104:105], v[244:245] op_sel_hi:[1,0]
	v_pk_mul_f32 v[150:151], v[98:99], v[244:245] op_sel_hi:[1,0]
	v_pk_mul_f32 v[152:153], v[100:101], v[244:245] op_sel_hi:[1,0]
	v_pk_mul_f32 v[122:123], v[122:123], v[154:155]
	v_pk_mul_f32 v[124:125], v[124:125], v[156:157]
	v_pk_mul_f32 v[118:119], v[118:119], v[158:159]
	v_pk_mul_f32 v[120:121], v[120:121], v[160:161]
	v_cvt_pk_bf16_f32 v166, v122, v123
	v_cvt_pk_bf16_f32 v167, v124, v125
	v_cvt_pk_bf16_f32 v168, v118, v119
	v_cvt_pk_bf16_f32 v169, v120, v121
	global_store_dwordx4 v190, v[166:169], s[10:11] sc1
	v_add_u32_e32 v190, s30, v190
	v_exp_f32_e32 v146, v146
	v_exp_f32_e32 v147, v147
	v_exp_f32_e32 v148, v148
	v_exp_f32_e32 v149, v149
	v_exp_f32_e32 v150, v150
	v_exp_f32_e32 v151, v151
	v_exp_f32_e32 v152, v152
	v_exp_f32_e32 v153, v153
	v_pk_mul_f32 v[102:103], v[102:103], v[90:91]
	v_pk_mul_f32 v[104:105], v[104:105], v[92:93]
	v_pk_mul_f32 v[98:99], v[98:99], v[86:87]
	v_pk_mul_f32 v[100:101], v[100:101], v[88:89]
	v_pk_fma_f32 v[146:147], v[146:147], v[244:245], v[244:245] op_sel:[0,1,1] op_sel_hi:[1,1,1]
	v_pk_fma_f32 v[148:149], v[148:149], v[244:245], v[244:245] op_sel:[0,1,1] op_sel_hi:[1,1,1]
	v_pk_fma_f32 v[150:151], v[150:151], v[244:245], v[244:245] op_sel:[0,1,1] op_sel_hi:[1,1,1]
	v_pk_fma_f32 v[152:153], v[152:153], v[244:245], v[244:245] op_sel:[0,1,1] op_sel_hi:[1,1,1]
	v_rcp_f32_e32 v146, v146
	v_rcp_f32_e32 v147, v147
	v_rcp_f32_e32 v148, v148
	v_rcp_f32_e32 v149, v149
	v_rcp_f32_e32 v150, v150
	v_rcp_f32_e32 v151, v151
	v_rcp_f32_e32 v152, v152
	v_rcp_f32_e32 v153, v153
	v_pk_mul_f32 v[154:155], v[82:83], v[246:247] op_sel_hi:[1,0]
	v_pk_mul_f32 v[156:157], v[84:85], v[246:247] op_sel_hi:[1,0]
	v_pk_mul_f32 v[158:159], v[78:79], v[246:247] op_sel_hi:[1,0]
	v_pk_mul_f32 v[160:161], v[80:81], v[246:247] op_sel_hi:[1,0]
	v_pk_mul_f32 v[102:103], v[102:103], v[146:147]
	v_pk_mul_f32 v[104:105], v[104:105], v[148:149]
	v_pk_mul_f32 v[98:99], v[98:99], v[150:151]
	v_pk_mul_f32 v[100:101], v[100:101], v[152:153]
	v_cvt_pk_bf16_f32 v162, v102, v103
	v_cvt_pk_bf16_f32 v163, v104, v105
	v_cvt_pk_bf16_f32 v164, v98, v99
	v_cvt_pk_bf16_f32 v165, v100, v101
	global_store_dwordx4 v190, v[162:165], s[10:11] sc1
	v_add_u32_e32 v190, s30, v190
	v_exp_f32_e32 v154, v154
	v_exp_f32_e32 v155, v155
	v_exp_f32_e32 v156, v156
	v_exp_f32_e32 v157, v157
	v_exp_f32_e32 v158, v158
	v_exp_f32_e32 v159, v159
	v_exp_f32_e32 v160, v160
	v_exp_f32_e32 v161, v161
	v_pk_mul_f32 v[82:83], v[82:83], v[70:71]
	v_pk_mul_f32 v[84:85], v[84:85], v[72:73]
	v_pk_mul_f32 v[78:79], v[78:79], v[66:67]
	v_pk_mul_f32 v[80:81], v[80:81], v[68:69]
; __device__ __forceinline__ unsigned cvt_pk_bf16(float lo, float hi) { unsigned r; asm volatile("v_cvt_pk_bf16_f32 %0, %1, %2" : "=v"(r) : "v"(lo), "v"(hi)); return r; }
; __device__ __forceinline__ float silu_f(float g) { return g * __builtin_amdgcn_rcpf(1.0f + __builtin_amdgcn_exp2f(g * -1.4426950408889634f)); }
;     __device__ __forceinline__ void operator()(const f32x4 (&acc)[2][2][4][2], const Unit& u, int wr, int wc, int fr, int fq) const {
;     ...
;             for (int m = 0; m < 4; ++m) { const int row = row0 + ai * HALF + m * 16; const float rs = rsv[ai][m];
;                 f32x4 g0 = acc[ai][0][m][0] * rs, g1 = acc[ai][0][m][1] * rs; const f32x4 t0 = acc[ai][1][m][0] * rs, t1 = acc[ai][1][m][1] * rs;
;                 if (silu) {
; #pragma unroll
;                     for (int j = 0; j < 4; ++j) { g0[j] = silu_f(g0[j]); g1[j] = silu_f(g1[j]); } }
;                 g0 = g0 * t0; g1 = g1 * t1;
;                 u32x4 w; w.x = cvt_pk_bf16(g0[0], g0[1]); w.y = cvt_pk_bf16(g0[2], g0[3]); w.z = cvt_pk_bf16(g1[0], g1[1]); w.w = cvt_pk_bf16(g1[2], g1[3]);
;                 *(u32x4*)(O + (size_t)row * ldc + col0 + (size_t)(row >> 12) * adj) = w; }
	v_pk_fma_f32 v[154:155], v[154:155], v[246:247], v[246:247] op_sel:[0,1,1] op_sel_hi:[1,1,1]
	v_pk_fma_f32 v[156:157], v[156:157], v[246:247], v[246:247] op_sel:[0,1,1] op_sel_hi:[1,1,1]
	v_pk_fma_f32 v[158:159], v[158:159], v[246:247], v[246:247] op_sel:[0,1,1] op_sel_hi:[1,1,1]
	v_pk_fma_f32 v[160:161], v[160:161], v[246:247], v[246:247] op_sel:[0,1,1] op_sel_hi:[1,1,1]
	v_rcp_f32_e32 v154, v154
	v_rcp_f32_e32 v155, v155
	v_rcp_f32_e32 v156, v156
	v_rcp_f32_e32 v157, v157
	v_rcp_f32_e32 v158, v158
	v_rcp_f32_e32 v159, v159
	v_rcp_f32_e32 v160, v160
	v_rcp_f32_e32 v161, v161
	v_pk_mul_f32 v[146:147], v[62:63], v[248:249] op_sel_hi:[1,0]
	v_pk_mul_f32 v[148:149], v[64:65], v[248:249] op_sel_hi:[1,0]
	v_pk_mul_f32 v[150:151], v[58:59], v[248:249] op_sel_hi:[1,0]
	v_pk_mul_f32 v[152:153], v[60:61], v[248:249] op_sel_hi:[1,0]
	v_pk_mul_f32 v[82:83], v[82:83], v[154:155]
	v_pk_mul_f32 v[84:85], v[84:85], v[156:157]
	v_pk_mul_f32 v[78:79], v[78:79], v[158:159]
	v_pk_mul_f32 v[80:81], v[80:81], v[160:161]
	v_cvt_pk_bf16_f32 v166, v82, v83
	v_cvt_pk_bf16_f32 v167, v84, v85
	v_cvt_pk_bf16_f32 v168, v78, v79
	v_cvt_pk_bf16_f32 v169, v80, v81
	global_store_dwordx4 v190, v[166:169], s[10:11] sc1
	v_add_u32_e32 v190, s31, v190
	v_exp_f32_e32 v146, v146
	v_exp_f32_e32 v147, v147
	v_exp_f32_e32 v148, v148
	v_exp_f32_e32 v149, v149
	v_exp_f32_e32 v150, v150
	v_exp_f32_e32 v151, v151
	v_exp_f32_e32 v152, v152
	v_exp_f32_e32 v153, v153
	v_pk_mul_f32 v[62:63], v[62:63], v[54:55]
	v_pk_mul_f32 v[64:65], v[64:65], v[56:57]
	v_pk_mul_f32 v[58:59], v[58:59], v[50:51]
	v_pk_mul_f32 v[60:61], v[60:61], v[52:53]
	v_pk_fma_f32 v[146:147], v[146:147], v[248:249], v[248:249] op_sel:[0,1,1] op_sel_hi:[1,1,1]
	v_pk_fma_f32 v[148:149], v[148:149], v[248:249], v[248:249] op_sel:[0,1,1] op_sel_hi:[1,1,1]
	v_pk_fma_f32 v[150:151], v[150:151], v[248:249], v[248:249] op_sel:[0,1,1] op_sel_hi:[1,1,1]
	v_pk_fma_f32 v[152:153], v[152:153], v[248:249], v[248:249] op_sel:[0,1,1] op_sel_hi:[1,1,1]
	v_rcp_f32_e32 v146, v146
	v_rcp_f32_e32 v147, v147
	v_rcp_f32_e32 v148, v148
	v_rcp_f32_e32 v149, v149
	v_rcp_f32_e32 v150, v150
	v_rcp_f32_e32 v151, v151
	v_rcp_f32_e32 v152, v152
	v_rcp_f32_e32 v153, v153
	v_pk_mul_f32 v[154:155], v[46:47], v[250:251] op_sel_hi:[1,0]
	v_pk_mul_f32 v[156:157], v[48:49], v[250:251] op_sel_hi:[1,0]
	v_pk_mul_f32 v[158:159], v[42:43], v[250:251] op_sel_hi:[1,0]
	v_pk_mul_f32 v[160:161], v[44:45], v[250:251] op_sel_hi:[1,0]
	v_pk_mul_f32 v[62:63], v[62:63], v[146:147]
	v_pk_mul_f32 v[64:65], v[64:65], v[148:149]
	v_pk_mul_f32 v[58:59], v[58:59], v[150:151]
	v_pk_mul_f32 v[60:61], v[60:61], v[152:153]
	v_cvt_pk_bf16_f32 v162, v62, v63
	v_cvt_pk_bf16_f32 v163, v64, v65
	v_cvt_pk_bf16_f32 v164, v58, v59
	v_cvt_pk_bf16_f32 v165, v60, v61
	global_store_dwordx4 v190, v[162:165], s[10:11] sc1
	v_add_u32_e32 v190, s30, v190
	v_exp_f32_e32 v154, v154
	v_exp_f32_e32 v155, v155
	v_exp_f32_e32 v156, v156
	v_exp_f32_e32 v157, v157
	v_exp_f32_e32 v158, v158
	v_exp_f32_e32 v159, v159
	v_exp_f32_e32 v160, v160
	v_exp_f32_e32 v161, v161
	v_pk_mul_f32 v[46:47], v[46:47], v[38:39]
	v_pk_mul_f32 v[48:49], v[48:49], v[40:41]
	v_pk_mul_f32 v[42:43], v[42:43], v[34:35]
	v_pk_mul_f32 v[44:45], v[44:45], v[36:37]
	v_pk_fma_f32 v[154:155], v[154:155], v[250:251], v[250:251] op_sel:[0,1,1] op_sel_hi:[1,1,1]
	v_pk_fma_f32 v[156:157], v[156:157], v[250:251], v[250:251] op_sel:[0,1,1] op_sel_hi:[1,1,1]
	v_pk_fma_f32 v[158:159], v[158:159], v[250:251], v[250:251] op_sel:[0,1,1] op_sel_hi:[1,1,1]
	v_pk_fma_f32 v[160:161], v[160:161], v[250:251], v[250:251] op_sel:[0,1,1] op_sel_hi:[1,1,1]
	v_rcp_f32_e32 v154, v154
	v_rcp_f32_e32 v155, v155
	v_rcp_f32_e32 v156, v156
	v_rcp_f32_e32 v157, v157
	v_rcp_f32_e32 v158, v158
; __device__ __forceinline__ unsigned cvt_pk_bf16(float lo, float hi) { unsigned r; asm volatile("v_cvt_pk_bf16_f32 %0, %1, %2" : "=v"(r) : "v"(lo), "v"(hi)); return r; }
; __device__ __forceinline__ float silu_f(float g) { return g * __builtin_amdgcn_rcpf(1.0f + __builtin_amdgcn_exp2f(g * -1.4426950408889634f)); }
;     __device__ __forceinline__ void operator()(const f32x4 (&acc)[2][2][4][2], const Unit& u, int wr, int wc, int fr, int fq) const {
;     ...
;             for (int m = 0; m < 4; ++m) { const int row = row0 + ai * HALF + m * 16; const float rs = rsv[ai][m];
;                 f32x4 g0 = acc[ai][0][m][0] * rs, g1 = acc[ai][0][m][1] * rs; const f32x4 t0 = acc[ai][1][m][0] * rs, t1 = acc[ai][1][m][1] * rs;
;                 if (silu) {
; #pragma unroll
;                     for (int j = 0; j < 4; ++j) { g0[j] = silu_f(g0[j]); g1[j] = silu_f(g1[j]); } }
;                 g0 = g0 * t0; g1 = g1 * t1;
;                 u32x4 w; w.x = cvt_pk_bf16(g0[0], g0[1]); w.y = cvt_pk_bf16(g0[2], g0[3]); w.z = cvt_pk_bf16(g1[0], g1[1]); w.w = cvt_pk_bf16(g1[2], g1[3]);
;                 *(u32x4*)(O + (size_t)row * ldc + col0 + (size_t)(row >> 12) * adj) = w; }
	v_rcp_f32_e32 v159, v159
	v_rcp_f32_e32 v160, v160
	v_rcp_f32_e32 v161, v161
	v_pk_mul_f32 v[146:147], v[30:31], v[252:253] op_sel_hi:[1,0]
	v_pk_mul_f32 v[148:149], v[32:33], v[252:253] op_sel_hi:[1,0]
	v_pk_mul_f32 v[150:151], v[26:27], v[252:253] op_sel_hi:[1,0]
	v_pk_mul_f32 v[152:153], v[28:29], v[252:253] op_sel_hi:[1,0]
	v_pk_mul_f32 v[46:47], v[46:47], v[154:155]
	v_pk_mul_f32 v[48:49], v[48:49], v[156:157]
	v_pk_mul_f32 v[42:43], v[42:43], v[158:159]
	v_pk_mul_f32 v[44:45], v[44:45], v[160:161]
	v_cvt_pk_bf16_f32 v166, v46, v47
	v_cvt_pk_bf16_f32 v167, v48, v49
	v_cvt_pk_bf16_f32 v168, v42, v43
	v_cvt_pk_bf16_f32 v169, v44, v45
	global_store_dwordx4 v190, v[166:169], s[10:11] sc1
	v_add_u32_e32 v190, s30, v190
	v_exp_f32_e32 v146, v146
	v_exp_f32_e32 v147, v147
	v_exp_f32_e32 v148, v148
	v_exp_f32_e32 v149, v149
	v_exp_f32_e32 v150, v150
	v_exp_f32_e32 v151, v151
	v_exp_f32_e32 v152, v152
	v_exp_f32_e32 v153, v153
	v_pk_mul_f32 v[30:31], v[30:31], v[22:23]
	v_pk_mul_f32 v[32:33], v[32:33], v[24:25]
	v_pk_mul_f32 v[26:27], v[26:27], v[18:19]
	v_pk_mul_f32 v[28:29], v[28:29], v[20:21]
	v_pk_fma_f32 v[146:147], v[146:147], v[252:253], v[252:253] op_sel:[0,1,1] op_sel_hi:[1,1,1]
	v_pk_fma_f32 v[148:149], v[148:149], v[252:253], v[252:253] op_sel:[0,1,1] op_sel_hi:[1,1,1]
	v_pk_fma_f32 v[150:151], v[150:151], v[252:253], v[252:253] op_sel:[0,1,1] op_sel_hi:[1,1,1]
	v_pk_fma_f32 v[152:153], v[152:153], v[252:253], v[252:253] op_sel:[0,1,1] op_sel_hi:[1,1,1]
	v_rcp_f32_e32 v146, v146
	v_rcp_f32_e32 v147, v147
	v_rcp_f32_e32 v148, v148
	v_rcp_f32_e32 v149, v149
	v_rcp_f32_e32 v150, v150
	v_rcp_f32_e32 v151, v151
	v_rcp_f32_e32 v152, v152
	v_rcp_f32_e32 v153, v153
	v_pk_mul_f32 v[154:155], v[14:15], v[214:215] op_sel_hi:[1,0]
	v_pk_mul_f32 v[156:157], v[16:17], v[214:215] op_sel_hi:[1,0]
	v_pk_mul_f32 v[158:159], v[10:11], v[214:215] op_sel_hi:[1,0]
	v_pk_mul_f32 v[160:161], v[12:13], v[214:215] op_sel_hi:[1,0]
	v_pk_mul_f32 v[30:31], v[30:31], v[146:147]
	v_pk_mul_f32 v[32:33], v[32:33], v[148:149]
	v_pk_mul_f32 v[26:27], v[26:27], v[150:151]
	v_pk_mul_f32 v[28:29], v[28:29], v[152:153]
	v_cvt_pk_bf16_f32 v162, v30, v31
	v_cvt_pk_bf16_f32 v163, v32, v33
	v_cvt_pk_bf16_f32 v164, v26, v27
	v_cvt_pk_bf16_f32 v165, v28, v29
	global_store_dwordx4 v190, v[162:165], s[10:11] sc1
	v_add_u32_e32 v190, s30, v190
	v_exp_f32_e32 v154, v154
	v_exp_f32_e32 v155, v155
	v_exp_f32_e32 v156, v156
	v_exp_f32_e32 v157, v157
	v_exp_f32_e32 v158, v158
	v_exp_f32_e32 v159, v159
	v_exp_f32_e32 v160, v160
	v_exp_f32_e32 v161, v161
	v_pk_mul_f32 v[14:15], v[14:15], v[6:7]
	v_pk_mul_f32 v[16:17], v[16:17], v[8:9]
	v_pk_mul_f32 v[10:11], v[10:11], v[2:3]
	v_pk_mul_f32 v[12:13], v[12:13], v[4:5]
	v_pk_fma_f32 v[154:155], v[154:155], v[214:215], v[214:215] op_sel:[0,1,1] op_sel_hi:[1,1,1]
	v_pk_fma_f32 v[156:157], v[156:157], v[214:215], v[214:215] op_sel:[0,1,1] op_sel_hi:[1,1,1]
	v_pk_fma_f32 v[158:159], v[158:159], v[214:215], v[214:215] op_sel:[0,1,1] op_sel_hi:[1,1,1]
	v_pk_fma_f32 v[160:161], v[160:161], v[214:215], v[214:215] op_sel:[0,1,1] op_sel_hi:[1,1,1]
	v_rcp_f32_e32 v154, v154
	v_rcp_f32_e32 v155, v155
	v_rcp_f32_e32 v156, v156
	v_rcp_f32_e32 v157, v157
	v_rcp_f32_e32 v158, v158
	v_rcp_f32_e32 v159, v159
	v_rcp_f32_e32 v160, v160
	v_rcp_f32_e32 v161, v161
	v_pk_mul_f32 v[14:15], v[14:15], v[154:155]
	v_pk_mul_f32 v[16:17], v[16:17], v[156:157]
	v_pk_mul_f32 v[10:11], v[10:11], v[158:159]
	v_pk_mul_f32 v[12:13], v[12:13], v[160:161]
	v_cvt_pk_bf16_f32 v166, v14, v15
	v_cvt_pk_bf16_f32 v167, v16, v17
	v_cvt_pk_bf16_f32 v168, v10, v11
	v_cvt_pk_bf16_f32 v169, v12, v13
	global_store_dwordx4 v190, v[166:169], s[10:11] sc1
	s_andn2_b64 vcc, exec, s[8:9]
	s_mov_b64 s[4:5], -1
	s_branch .Lep_join
